# stack v139 + last layer: dead bf16 residual-copy stores in the P8 epilogue suppressed
# speedup vs baseline: 1.0034x; 1.0034x over previous
.LBB0_1029:
	v_readlane_b32 s54, v255, 25
	s_cmp_eq_u32 s54, 3
	s_cselect_b64 s[54:55], 0, -1
	s_lshl_b32 s2, s45, 8
	v_readlane_b32 s3, v253, 62
	v_mov_b32_e32 v130, v169
	s_add_i32 s2, s2, s3
	v_mov_b32_e32 v132, v168
	v_add_u32_e32 v162, s2, v130
	s_lshl_b32 s2, s26, 8
	v_readlane_b32 s18, v255, 3
	s_ashr_i32 s3, s2, 31
	v_lshlrev_b32_e32 v130, 3, v132
	v_readlane_b32 s19, v255, 4
	v_ashrrev_i32_e32 v131, 31, v130
	s_or_b64 s[18:19], s[2:3], s[18:19]
	v_lshl_add_u64 v[160:161], s[18:19], 0, v[130:131]
	s_lshl_b32 s18, s26, 2
	s_ashr_i32 s19, s18, 31
	s_lshl_b64 s[2:3], s[2:3], 2
	s_add_u32 s2, s38, s2
	s_addc_u32 s3, s39, s3
	v_ashrrev_i32_e32 v163, 31, v162
	v_lshl_add_u64 v[164:165], v[130:131], 2, s[2:3]
	v_lshlrev_b64 v[130:131], 12, v[162:163]
	v_lshl_add_u64 v[130:131], v[164:165], 0, v[130:131]
	global_load_dwordx4 v[180:183], v[130:131], off offset:16
	global_load_dwordx4 v[184:187], v[130:131], off
	global_load_dwordx4 v[146:149], v[130:131], off offset:528
	global_load_dwordx4 v[188:191], v[130:131], off offset:512
	v_and_b32_e32 v134, 64, v209
	v_xor_b32_e32 v133, 16, v209
	v_add_u32_e32 v134, 64, v134
	v_cmp_lt_i32_e32 vcc, v133, v134
	v_add_u32_e32 v166, 16, v162
	v_ashrrev_i32_e32 v167, 31, v166
	v_cndmask_b32_e32 v133, v209, v133, vcc
	v_lshlrev_b32_e32 v173, 2, v133
	v_xor_b32_e32 v133, 32, v209
	v_cmp_lt_i32_e32 vcc, v133, v134
	v_lshlrev_b64 v[130:131], 12, v[166:167]
	v_lshl_add_u64 v[134:135], v[164:165], 0, v[130:131]
	v_cndmask_b32_e32 v133, v209, v133, vcc
	v_lshlrev_b32_e32 v172, 2, v133
	v_cmp_eq_u32_e32 vcc, 0, v132
	global_load_dwordx4 v[138:141], v[134:135], off offset:16
	global_load_dwordx4 v[142:145], v[134:135], off
	global_load_dwordx4 v[130:133], v[134:135], off offset:528
	s_nop 0
	global_load_dwordx4 v[134:137], v[134:135], off offset:512
	v_lshlrev_b64 v[174:175], 10, v[162:163]
	v_lshl_add_u64 v[174:175], v[160:161], 0, v[174:175]
	s_waitcnt vmcnt(0)
	v_pk_add_f32 v[122:123], v[122:123], v[180:181]
	v_pk_add_f32 v[126:127], v[126:127], v[184:185]
	v_pk_add_f32 v[128:129], v[128:129], v[186:187]
	v_mul_f32_e32 v186, v127, v127
	v_fmac_f32_e32 v186, v126, v126
	v_fmac_f32_e32 v186, v128, v128
	v_fmac_f32_e32 v186, v129, v129
	v_fmac_f32_e32 v186, v122, v122
	v_pk_add_f32 v[124:125], v[124:125], v[182:183]
	v_fmac_f32_e32 v186, v123, v123
	v_fmac_f32_e32 v186, v124, v124
	v_fmac_f32_e32 v186, v125, v125
	v_pk_add_f32 v[118:119], v[118:119], v[188:189]
	v_pk_add_f32 v[120:121], v[120:121], v[190:191]
	v_fmac_f32_e32 v186, v118, v118
	v_fmac_f32_e32 v186, v119, v119
	v_fmac_f32_e32 v186, v120, v120
	v_fmac_f32_e32 v186, v121, v121
	v_pk_add_f32 v[114:115], v[114:115], v[146:147]
	v_pk_add_f32 v[116:117], v[116:117], v[148:149]
	v_fmac_f32_e32 v186, v114, v114
	v_fmac_f32_e32 v186, v115, v115
	v_lshl_add_u64 v[184:185], v[174:175], 2, s[4:5]
	v_fmac_f32_e32 v186, v116, v116
	global_store_dwordx4 v[184:185], v[126:129], off
	global_store_dwordx4 v[184:185], v[122:125], off offset:16
	v_fmac_f32_e32 v186, v117, v117
	v_cvt_pk_bf16_f32 v126, v126, v127
	v_cvt_pk_bf16_f32 v127, v128, v129
	v_cvt_pk_bf16_f32 v128, v122, v123
	v_cvt_pk_bf16_f32 v129, v124, v125
	v_lshl_add_u64 v[122:123], v[174:175], 1, s[0:1]
	s_mov_b64 exec, s[54:55]
	global_store_dwordx4 v[122:123], v[126:129], off
	s_mov_b64 exec, -1
	global_store_dwordx4 v[184:185], v[118:121], off offset:512
	global_store_dwordx4 v[184:185], v[114:117], off offset:528
	s_nop 0
	v_cvt_pk_bf16_f32 v118, v118, v119
	v_cvt_pk_bf16_f32 v119, v120, v121
	v_cvt_pk_bf16_f32 v120, v114, v115
	ds_bpermute_b32 v114, v173, v186
	v_cvt_pk_bf16_f32 v121, v116, v117
	s_mov_b64 exec, s[54:55]
	global_store_dwordx4 v[122:123], v[118:121], off offset:256
	s_mov_b64 exec, -1
	s_waitcnt lgkmcnt(0)
	v_add_f32_e32 v114, v186, v114
	ds_bpermute_b32 v115, v172, v114
	s_and_saveexec_b64 s[2:3], vcc
	s_cbranch_execz .LBB0_1031
	v_lshlrev_b64 v[116:117], 6, v[162:163]
	v_lshl_add_u64 v[116:117], s[6:7], 0, v[116:117]
	v_readlane_b32 s9, v255, 14
	v_lshl_add_u64 v[116:117], s[18:19], 2, v[116:117]
	s_lshl_b32 s26, s9, 2
	v_lshl_add_u64 v[116:117], v[116:117], 0, s[26:27]
	s_waitcnt lgkmcnt(0)
	v_add_f32_e32 v114, v114, v115
	global_store_dword v[116:117], v114, off
.LBB0_1031:
	s_or_b64 exec, exec, s[2:3]
	v_pk_add_f32 v[110:111], v[110:111], v[142:143]
	v_pk_add_f32 v[112:113], v[112:113], v[144:145]
	v_mul_f32_e32 v118, v111, v111
	v_fmac_f32_e32 v118, v110, v110
	v_fmac_f32_e32 v118, v112, v112
	v_fmac_f32_e32 v118, v113, v113
	v_pk_add_f32 v[106:107], v[106:107], v[138:139]
	v_pk_add_f32 v[108:109], v[108:109], v[140:141]
	v_fmac_f32_e32 v118, v106, v106
	v_fmac_f32_e32 v118, v107, v107
	v_fmac_f32_e32 v118, v108, v108
	v_fmac_f32_e32 v118, v109, v109
	v_pk_add_f32 v[102:103], v[102:103], v[134:135]
	s_waitcnt lgkmcnt(0)
	v_lshlrev_b64 v[114:115], 10, v[166:167]
	v_fmac_f32_e32 v118, v102, v102
	v_lshl_add_u64 v[114:115], v[160:161], 0, v[114:115]
	v_pk_add_f32 v[104:105], v[104:105], v[136:137]
	v_fmac_f32_e32 v118, v103, v103
	v_lshl_add_u64 v[116:117], v[114:115], 2, s[4:5]
	v_fmac_f32_e32 v118, v104, v104
	global_store_dwordx4 v[116:117], v[110:113], off
	global_store_dwordx4 v[116:117], v[106:109], off offset:16
	v_fmac_f32_e32 v118, v105, v105
	v_cvt_pk_bf16_f32 v110, v110, v111
	v_cvt_pk_bf16_f32 v111, v112, v113
	v_cvt_pk_bf16_f32 v112, v106, v107
	v_pk_add_f32 v[106:107], v[98:99], v[130:131]
	v_cvt_pk_bf16_f32 v113, v108, v109
	v_fmac_f32_e32 v118, v106, v106
	v_pk_add_f32 v[108:109], v[100:101], v[132:133]
	v_fmac_f32_e32 v118, v107, v107
	v_fmac_f32_e32 v118, v108, v108
	v_fmac_f32_e32 v118, v109, v109
	ds_bpermute_b32 v98, v173, v118
	v_lshl_add_u64 v[114:115], v[114:115], 1, s[0:1]
	s_mov_b64 exec, s[54:55]
	global_store_dwordx4 v[114:115], v[110:113], off
	s_mov_b64 exec, -1
	global_store_dwordx4 v[116:117], v[102:105], off offset:512
	global_store_dwordx4 v[116:117], v[106:109], off offset:528
	v_cvt_pk_bf16_f32 v100, v102, v103
	v_cvt_pk_bf16_f32 v101, v104, v105
	s_waitcnt lgkmcnt(0)
	v_add_f32_e32 v98, v118, v98
	ds_bpermute_b32 v99, v172, v98
	v_cvt_pk_bf16_f32 v102, v106, v107
	v_cvt_pk_bf16_f32 v103, v108, v109
	s_mov_b64 exec, s[54:55]
	global_store_dwordx4 v[114:115], v[100:103], off offset:256
	s_mov_b64 exec, -1
	s_and_saveexec_b64 s[2:3], vcc
	s_cbranch_execz .LBB0_1033
	v_lshlrev_b64 v[100:101], 6, v[166:167]
	v_lshl_add_u64 v[100:101], s[6:7], 0, v[100:101]
	v_readlane_b32 s9, v255, 14
	v_lshl_add_u64 v[100:101], s[18:19], 2, v[100:101]
	s_lshl_b32 s26, s9, 2
	v_lshl_add_u64 v[100:101], v[100:101], 0, s[26:27]
	s_waitcnt lgkmcnt(0)
	v_add_f32_e32 v98, v98, v99
	global_store_dword v[100:101], v98, off
.LBB0_1033:
	s_or_b64 exec, exec, s[2:3]
	v_add_u32_e32 v120, 32, v162
	v_ashrrev_i32_e32 v121, 31, v120
	s_waitcnt lgkmcnt(0)
	v_lshlrev_b64 v[98:99], 12, v[120:121]
	v_lshl_add_u64 v[98:99], v[164:165], 0, v[98:99]
	global_load_dwordx4 v[122:125], v[98:99], off offset:16
	global_load_dwordx4 v[126:129], v[98:99], off
	global_load_dwordx4 v[114:117], v[98:99], off offset:528
	global_load_dwordx4 v[130:133], v[98:99], off offset:512
	v_add_u32_e32 v118, 48, v162
	v_ashrrev_i32_e32 v119, 31, v118
	v_lshlrev_b64 v[98:99], 12, v[118:119]
	v_lshl_add_u64 v[102:103], v[164:165], 0, v[98:99]
	global_load_dwordx4 v[106:109], v[102:103], off offset:16
	global_load_dwordx4 v[110:113], v[102:103], off
	global_load_dwordx4 v[98:101], v[102:103], off offset:528
	s_nop 0
	global_load_dwordx4 v[102:105], v[102:103], off offset:512
	v_lshlrev_b64 v[134:135], 10, v[120:121]
	v_lshl_add_u64 v[134:135], v[160:161], 0, v[134:135]
	s_waitcnt vmcnt(7)
	v_pk_add_f32 v[90:91], v[90:91], v[122:123]
	s_waitcnt vmcnt(6)
	v_pk_add_f32 v[94:95], v[94:95], v[126:127]
	v_pk_add_f32 v[96:97], v[96:97], v[128:129]
	v_mul_f32_e32 v128, v95, v95
	v_fmac_f32_e32 v128, v94, v94
	v_fmac_f32_e32 v128, v96, v96
	v_fmac_f32_e32 v128, v97, v97
	v_fmac_f32_e32 v128, v90, v90
	v_pk_add_f32 v[92:93], v[92:93], v[124:125]
	v_fmac_f32_e32 v128, v91, v91
	v_fmac_f32_e32 v128, v92, v92
	v_fmac_f32_e32 v128, v93, v93
	s_waitcnt vmcnt(4)
	v_pk_add_f32 v[86:87], v[86:87], v[130:131]
	v_pk_add_f32 v[88:89], v[88:89], v[132:133]
	v_fmac_f32_e32 v128, v86, v86
	v_fmac_f32_e32 v128, v87, v87
	v_fmac_f32_e32 v128, v88, v88
	v_fmac_f32_e32 v128, v89, v89
	v_pk_add_f32 v[82:83], v[82:83], v[114:115]
	v_pk_add_f32 v[84:85], v[84:85], v[116:117]
	v_fmac_f32_e32 v128, v82, v82
	v_fmac_f32_e32 v128, v83, v83
	v_lshl_add_u64 v[126:127], v[134:135], 2, s[4:5]
	v_fmac_f32_e32 v128, v84, v84
	global_store_dwordx4 v[126:127], v[94:97], off
	global_store_dwordx4 v[126:127], v[90:93], off offset:16
	v_fmac_f32_e32 v128, v85, v85
	v_cvt_pk_bf16_f32 v94, v94, v95
	v_cvt_pk_bf16_f32 v95, v96, v97
	v_cvt_pk_bf16_f32 v96, v90, v91
	v_cvt_pk_bf16_f32 v97, v92, v93
	v_lshl_add_u64 v[90:91], v[134:135], 1, s[0:1]
	s_mov_b64 exec, s[54:55]
	global_store_dwordx4 v[90:91], v[94:97], off
	s_mov_b64 exec, -1
	global_store_dwordx4 v[126:127], v[86:89], off offset:512
	global_store_dwordx4 v[126:127], v[82:85], off offset:528
	s_nop 0
	v_cvt_pk_bf16_f32 v86, v86, v87
	v_cvt_pk_bf16_f32 v87, v88, v89
	v_cvt_pk_bf16_f32 v88, v82, v83
	ds_bpermute_b32 v82, v173, v128
	v_cvt_pk_bf16_f32 v89, v84, v85
	s_mov_b64 exec, s[54:55]
	global_store_dwordx4 v[90:91], v[86:89], off offset:256
	s_mov_b64 exec, -1
	s_waitcnt lgkmcnt(0)
	v_add_f32_e32 v82, v128, v82
	ds_bpermute_b32 v83, v172, v82
	s_and_saveexec_b64 s[2:3], vcc
	s_cbranch_execz .LBB0_1035
	v_lshlrev_b64 v[84:85], 6, v[120:121]
	v_lshl_add_u64 v[84:85], s[6:7], 0, v[84:85]
	v_readlane_b32 s9, v255, 14
	v_lshl_add_u64 v[84:85], s[18:19], 2, v[84:85]
	s_lshl_b32 s26, s9, 2
	v_lshl_add_u64 v[84:85], v[84:85], 0, s[26:27]
	s_waitcnt lgkmcnt(0)
	v_add_f32_e32 v82, v82, v83
	global_store_dword v[84:85], v82, off
.LBB0_1035:
	s_or_b64 exec, exec, s[2:3]
	s_waitcnt vmcnt(8)
	v_pk_add_f32 v[78:79], v[78:79], v[110:111]
	v_pk_add_f32 v[80:81], v[80:81], v[112:113]
	v_mul_f32_e32 v86, v79, v79
	v_fmac_f32_e32 v86, v78, v78
	v_fmac_f32_e32 v86, v80, v80
	v_fmac_f32_e32 v86, v81, v81
	v_pk_add_f32 v[74:75], v[74:75], v[106:107]
	v_pk_add_f32 v[76:77], v[76:77], v[108:109]
	v_fmac_f32_e32 v86, v74, v74
	v_fmac_f32_e32 v86, v75, v75
	v_fmac_f32_e32 v86, v76, v76
	v_fmac_f32_e32 v86, v77, v77
	s_waitcnt vmcnt(6)
	v_pk_add_f32 v[70:71], v[70:71], v[102:103]
	s_waitcnt lgkmcnt(0)
	v_lshlrev_b64 v[82:83], 10, v[118:119]
	v_fmac_f32_e32 v86, v70, v70
	v_lshl_add_u64 v[82:83], v[160:161], 0, v[82:83]
	v_pk_add_f32 v[72:73], v[72:73], v[104:105]
	v_fmac_f32_e32 v86, v71, v71
	v_lshl_add_u64 v[84:85], v[82:83], 2, s[4:5]
	v_fmac_f32_e32 v86, v72, v72
	global_store_dwordx4 v[84:85], v[78:81], off
	global_store_dwordx4 v[84:85], v[74:77], off offset:16
	v_fmac_f32_e32 v86, v73, v73
	v_cvt_pk_bf16_f32 v78, v78, v79
	v_cvt_pk_bf16_f32 v79, v80, v81
	v_cvt_pk_bf16_f32 v80, v74, v75
	v_pk_add_f32 v[74:75], v[66:67], v[98:99]
	v_cvt_pk_bf16_f32 v81, v76, v77
	v_fmac_f32_e32 v86, v74, v74
	v_pk_add_f32 v[76:77], v[68:69], v[100:101]
	v_fmac_f32_e32 v86, v75, v75
	v_fmac_f32_e32 v86, v76, v76
	v_fmac_f32_e32 v86, v77, v77
	ds_bpermute_b32 v66, v173, v86
	v_lshl_add_u64 v[82:83], v[82:83], 1, s[0:1]
	s_mov_b64 exec, s[54:55]
	global_store_dwordx4 v[82:83], v[78:81], off
	s_mov_b64 exec, -1
	global_store_dwordx4 v[84:85], v[70:73], off offset:512
	global_store_dwordx4 v[84:85], v[74:77], off offset:528
	v_cvt_pk_bf16_f32 v68, v70, v71
	v_cvt_pk_bf16_f32 v69, v72, v73
	s_waitcnt lgkmcnt(0)
	v_add_f32_e32 v66, v86, v66
	ds_bpermute_b32 v67, v172, v66
	v_cvt_pk_bf16_f32 v70, v74, v75
	v_cvt_pk_bf16_f32 v71, v76, v77
	s_mov_b64 exec, s[54:55]
	global_store_dwordx4 v[82:83], v[68:71], off offset:256
	s_mov_b64 exec, -1
	s_and_saveexec_b64 s[2:3], vcc
	s_cbranch_execz .LBB0_1037
	v_lshlrev_b64 v[68:69], 6, v[118:119]
	v_lshl_add_u64 v[68:69], s[6:7], 0, v[68:69]
	v_readlane_b32 s9, v255, 14
	v_lshl_add_u64 v[68:69], s[18:19], 2, v[68:69]
	s_lshl_b32 s26, s9, 2
	v_lshl_add_u64 v[68:69], v[68:69], 0, s[26:27]
	s_waitcnt lgkmcnt(0)
	v_add_f32_e32 v66, v66, v67
	global_store_dword v[68:69], v66, off
.LBB0_1037:
	s_or_b64 exec, exec, s[2:3]
	v_add_u32_e32 v88, 0x80, v162
	v_ashrrev_i32_e32 v89, 31, v88
	s_waitcnt lgkmcnt(0)
	v_lshlrev_b64 v[66:67], 12, v[88:89]
	v_lshl_add_u64 v[66:67], v[164:165], 0, v[66:67]
	global_load_dwordx4 v[90:93], v[66:67], off offset:16
	global_load_dwordx4 v[94:97], v[66:67], off
	global_load_dwordx4 v[82:85], v[66:67], off offset:528
	global_load_dwordx4 v[98:101], v[66:67], off offset:512
	v_add_u32_e32 v86, 0x90, v162
	v_ashrrev_i32_e32 v87, 31, v86
	v_lshlrev_b64 v[66:67], 12, v[86:87]
	v_lshl_add_u64 v[70:71], v[164:165], 0, v[66:67]
	global_load_dwordx4 v[74:77], v[70:71], off offset:16
	global_load_dwordx4 v[78:81], v[70:71], off
	global_load_dwordx4 v[66:69], v[70:71], off offset:528
	s_nop 0
	global_load_dwordx4 v[70:73], v[70:71], off offset:512
	v_lshlrev_b64 v[102:103], 10, v[88:89]
	v_lshl_add_u64 v[102:103], v[160:161], 0, v[102:103]
	s_waitcnt vmcnt(7)
	v_pk_add_f32 v[58:59], v[58:59], v[90:91]
	s_waitcnt vmcnt(6)
	v_pk_add_f32 v[62:63], v[62:63], v[94:95]
	v_pk_add_f32 v[64:65], v[64:65], v[96:97]
	v_mul_f32_e32 v96, v63, v63
	v_fmac_f32_e32 v96, v62, v62
	v_fmac_f32_e32 v96, v64, v64
	v_fmac_f32_e32 v96, v65, v65
	v_fmac_f32_e32 v96, v58, v58
	v_pk_add_f32 v[60:61], v[60:61], v[92:93]
	v_fmac_f32_e32 v96, v59, v59
	v_fmac_f32_e32 v96, v60, v60
	v_fmac_f32_e32 v96, v61, v61
	s_waitcnt vmcnt(4)
	v_pk_add_f32 v[54:55], v[54:55], v[98:99]
	v_pk_add_f32 v[56:57], v[56:57], v[100:101]
	v_fmac_f32_e32 v96, v54, v54
	v_fmac_f32_e32 v96, v55, v55
	v_fmac_f32_e32 v96, v56, v56
	v_fmac_f32_e32 v96, v57, v57
	v_pk_add_f32 v[50:51], v[50:51], v[82:83]
	v_pk_add_f32 v[52:53], v[52:53], v[84:85]
	v_fmac_f32_e32 v96, v50, v50
	v_fmac_f32_e32 v96, v51, v51
	v_lshl_add_u64 v[94:95], v[102:103], 2, s[4:5]
	v_fmac_f32_e32 v96, v52, v52
	global_store_dwordx4 v[94:95], v[62:65], off
	global_store_dwordx4 v[94:95], v[58:61], off offset:16
	v_fmac_f32_e32 v96, v53, v53
	v_cvt_pk_bf16_f32 v62, v62, v63
	v_cvt_pk_bf16_f32 v63, v64, v65
	v_cvt_pk_bf16_f32 v64, v58, v59
	v_cvt_pk_bf16_f32 v65, v60, v61
	v_lshl_add_u64 v[58:59], v[102:103], 1, s[0:1]
	s_mov_b64 exec, s[54:55]
	global_store_dwordx4 v[58:59], v[62:65], off
	s_mov_b64 exec, -1
	global_store_dwordx4 v[94:95], v[54:57], off offset:512
	global_store_dwordx4 v[94:95], v[50:53], off offset:528
	s_nop 0
	v_cvt_pk_bf16_f32 v54, v54, v55
	v_cvt_pk_bf16_f32 v55, v56, v57
	v_cvt_pk_bf16_f32 v56, v50, v51
	ds_bpermute_b32 v50, v173, v96
	v_cvt_pk_bf16_f32 v57, v52, v53
	s_mov_b64 exec, s[54:55]
	global_store_dwordx4 v[58:59], v[54:57], off offset:256
	s_mov_b64 exec, -1
	s_waitcnt lgkmcnt(0)
	v_add_f32_e32 v50, v96, v50
	ds_bpermute_b32 v51, v172, v50
	s_and_saveexec_b64 s[2:3], vcc
	s_cbranch_execz .LBB0_1039
	v_lshlrev_b64 v[52:53], 6, v[88:89]
	v_lshl_add_u64 v[52:53], s[6:7], 0, v[52:53]
	v_readlane_b32 s9, v255, 14
	v_lshl_add_u64 v[52:53], s[18:19], 2, v[52:53]
	s_lshl_b32 s26, s9, 2
	v_lshl_add_u64 v[52:53], v[52:53], 0, s[26:27]
	s_waitcnt lgkmcnt(0)
	v_add_f32_e32 v50, v50, v51
	global_store_dword v[52:53], v50, off
.LBB0_1039:
	s_or_b64 exec, exec, s[2:3]
	s_waitcnt vmcnt(8)
	v_pk_add_f32 v[46:47], v[46:47], v[78:79]
	v_pk_add_f32 v[48:49], v[48:49], v[80:81]
	v_mul_f32_e32 v54, v47, v47
	v_fmac_f32_e32 v54, v46, v46
	v_fmac_f32_e32 v54, v48, v48
	v_fmac_f32_e32 v54, v49, v49
	v_pk_add_f32 v[42:43], v[42:43], v[74:75]
	v_pk_add_f32 v[44:45], v[44:45], v[76:77]
	v_fmac_f32_e32 v54, v42, v42
	v_fmac_f32_e32 v54, v43, v43
	v_fmac_f32_e32 v54, v44, v44
	v_fmac_f32_e32 v54, v45, v45
	s_waitcnt vmcnt(6)
	v_pk_add_f32 v[38:39], v[38:39], v[70:71]
	s_waitcnt lgkmcnt(0)
	v_lshlrev_b64 v[50:51], 10, v[86:87]
	v_fmac_f32_e32 v54, v38, v38
	v_lshl_add_u64 v[50:51], v[160:161], 0, v[50:51]
	v_pk_add_f32 v[40:41], v[40:41], v[72:73]
	v_fmac_f32_e32 v54, v39, v39
	v_lshl_add_u64 v[52:53], v[50:51], 2, s[4:5]
	v_fmac_f32_e32 v54, v40, v40
	global_store_dwordx4 v[52:53], v[46:49], off
	global_store_dwordx4 v[52:53], v[42:45], off offset:16
	v_fmac_f32_e32 v54, v41, v41
	v_cvt_pk_bf16_f32 v46, v46, v47
	v_cvt_pk_bf16_f32 v47, v48, v49
	v_cvt_pk_bf16_f32 v48, v42, v43
	v_pk_add_f32 v[42:43], v[34:35], v[66:67]
	v_cvt_pk_bf16_f32 v49, v44, v45
	v_fmac_f32_e32 v54, v42, v42
	v_pk_add_f32 v[44:45], v[36:37], v[68:69]
	v_fmac_f32_e32 v54, v43, v43
	v_fmac_f32_e32 v54, v44, v44
	v_fmac_f32_e32 v54, v45, v45
	ds_bpermute_b32 v34, v173, v54
	v_lshl_add_u64 v[50:51], v[50:51], 1, s[0:1]
	s_mov_b64 exec, s[54:55]
	global_store_dwordx4 v[50:51], v[46:49], off
	s_mov_b64 exec, -1
	global_store_dwordx4 v[52:53], v[38:41], off offset:512
	global_store_dwordx4 v[52:53], v[42:45], off offset:528
	v_cvt_pk_bf16_f32 v36, v38, v39
	v_cvt_pk_bf16_f32 v37, v40, v41
	s_waitcnt lgkmcnt(0)
	v_add_f32_e32 v34, v54, v34
	ds_bpermute_b32 v35, v172, v34
	v_cvt_pk_bf16_f32 v38, v42, v43
	v_cvt_pk_bf16_f32 v39, v44, v45
	s_mov_b64 exec, s[54:55]
	global_store_dwordx4 v[50:51], v[36:39], off offset:256
	s_mov_b64 exec, -1
	s_and_saveexec_b64 s[2:3], vcc
	s_cbranch_execz .LBB0_1041
	v_lshlrev_b64 v[36:37], 6, v[86:87]
	v_lshl_add_u64 v[36:37], s[6:7], 0, v[36:37]
	v_readlane_b32 s9, v255, 14
	v_lshl_add_u64 v[36:37], s[18:19], 2, v[36:37]
	s_lshl_b32 s26, s9, 2
	v_lshl_add_u64 v[36:37], v[36:37], 0, s[26:27]
	s_waitcnt lgkmcnt(0)
	v_add_f32_e32 v34, v34, v35
	global_store_dword v[36:37], v34, off
.LBB0_1041:
	s_or_b64 exec, exec, s[2:3]
	v_add_u32_e32 v56, 0xa0, v162
	v_ashrrev_i32_e32 v57, 31, v56
	s_waitcnt lgkmcnt(0)
	v_lshlrev_b64 v[34:35], 12, v[56:57]
	v_lshl_add_u64 v[34:35], v[164:165], 0, v[34:35]
	global_load_dwordx4 v[58:61], v[34:35], off offset:16
	global_load_dwordx4 v[62:65], v[34:35], off
	global_load_dwordx4 v[50:53], v[34:35], off offset:528
	global_load_dwordx4 v[66:69], v[34:35], off offset:512
	v_add_u32_e32 v54, 0xb0, v162
	v_ashrrev_i32_e32 v55, 31, v54
	v_lshlrev_b64 v[34:35], 12, v[54:55]
	v_lshl_add_u64 v[38:39], v[164:165], 0, v[34:35]
	global_load_dwordx4 v[42:45], v[38:39], off offset:16
	global_load_dwordx4 v[46:49], v[38:39], off
	global_load_dwordx4 v[34:37], v[38:39], off offset:528
	s_nop 0
	global_load_dwordx4 v[38:41], v[38:39], off offset:512
	v_lshlrev_b64 v[70:71], 10, v[56:57]
	v_lshl_add_u64 v[70:71], v[160:161], 0, v[70:71]
	s_waitcnt vmcnt(7)
	v_pk_add_f32 v[26:27], v[26:27], v[58:59]
	s_waitcnt vmcnt(6)
	v_pk_add_f32 v[30:31], v[30:31], v[62:63]
	v_pk_add_f32 v[32:33], v[32:33], v[64:65]
	v_mul_f32_e32 v64, v31, v31
	v_fmac_f32_e32 v64, v30, v30
	v_fmac_f32_e32 v64, v32, v32
	v_fmac_f32_e32 v64, v33, v33
	v_fmac_f32_e32 v64, v26, v26
	v_pk_add_f32 v[28:29], v[28:29], v[60:61]
	v_fmac_f32_e32 v64, v27, v27
	v_fmac_f32_e32 v64, v28, v28
	v_fmac_f32_e32 v64, v29, v29
	s_waitcnt vmcnt(4)
	v_pk_add_f32 v[22:23], v[22:23], v[66:67]
	v_pk_add_f32 v[24:25], v[24:25], v[68:69]
	v_fmac_f32_e32 v64, v22, v22
	v_fmac_f32_e32 v64, v23, v23
	v_fmac_f32_e32 v64, v24, v24
	v_fmac_f32_e32 v64, v25, v25
	v_pk_add_f32 v[18:19], v[18:19], v[50:51]
	v_pk_add_f32 v[20:21], v[20:21], v[52:53]
	v_fmac_f32_e32 v64, v18, v18
	v_fmac_f32_e32 v64, v19, v19
	v_lshl_add_u64 v[62:63], v[70:71], 2, s[4:5]
	v_fmac_f32_e32 v64, v20, v20
	global_store_dwordx4 v[62:63], v[30:33], off
	global_store_dwordx4 v[62:63], v[26:29], off offset:16
	v_fmac_f32_e32 v64, v21, v21
	v_cvt_pk_bf16_f32 v30, v30, v31
	v_cvt_pk_bf16_f32 v31, v32, v33
	v_cvt_pk_bf16_f32 v32, v26, v27
	v_cvt_pk_bf16_f32 v33, v28, v29
	v_lshl_add_u64 v[26:27], v[70:71], 1, s[0:1]
	s_mov_b64 exec, s[54:55]
	global_store_dwordx4 v[26:27], v[30:33], off
	s_mov_b64 exec, -1
	global_store_dwordx4 v[62:63], v[22:25], off offset:512
	global_store_dwordx4 v[62:63], v[18:21], off offset:528
	s_nop 0
	v_cvt_pk_bf16_f32 v22, v22, v23
	v_cvt_pk_bf16_f32 v23, v24, v25
	v_cvt_pk_bf16_f32 v24, v18, v19
	ds_bpermute_b32 v18, v173, v64
	v_cvt_pk_bf16_f32 v25, v20, v21
	s_mov_b64 exec, s[54:55]
	global_store_dwordx4 v[26:27], v[22:25], off offset:256
	s_mov_b64 exec, -1
	s_waitcnt lgkmcnt(0)
	v_add_f32_e32 v18, v64, v18
	ds_bpermute_b32 v19, v172, v18
	s_and_saveexec_b64 s[2:3], vcc
	s_cbranch_execz .LBB0_1043
	v_lshlrev_b64 v[20:21], 6, v[56:57]
	v_lshl_add_u64 v[20:21], s[6:7], 0, v[20:21]
	v_readlane_b32 s9, v255, 14
	v_lshl_add_u64 v[20:21], s[18:19], 2, v[20:21]
	s_lshl_b32 s26, s9, 2
	v_lshl_add_u64 v[20:21], v[20:21], 0, s[26:27]
	s_waitcnt lgkmcnt(0)
	v_add_f32_e32 v18, v18, v19
	global_store_dword v[20:21], v18, off
.LBB0_1043:
	s_or_b64 exec, exec, s[2:3]
	s_waitcnt vmcnt(8)
	v_pk_add_f32 v[14:15], v[14:15], v[46:47]
	v_pk_add_f32 v[16:17], v[16:17], v[48:49]
	v_mul_f32_e32 v22, v15, v15
	v_fmac_f32_e32 v22, v14, v14
	v_fmac_f32_e32 v22, v16, v16
	v_fmac_f32_e32 v22, v17, v17
	v_pk_add_f32 v[10:11], v[10:11], v[42:43]
	v_pk_add_f32 v[12:13], v[12:13], v[44:45]
	v_fmac_f32_e32 v22, v10, v10
	v_fmac_f32_e32 v22, v11, v11
	v_fmac_f32_e32 v22, v12, v12
	v_fmac_f32_e32 v22, v13, v13
	s_waitcnt vmcnt(6)
	v_pk_add_f32 v[6:7], v[6:7], v[38:39]
	s_waitcnt lgkmcnt(0)
	v_lshlrev_b64 v[18:19], 10, v[54:55]
	v_fmac_f32_e32 v22, v6, v6
	v_lshl_add_u64 v[18:19], v[160:161], 0, v[18:19]
	v_pk_add_f32 v[8:9], v[8:9], v[40:41]
	v_fmac_f32_e32 v22, v7, v7
	v_lshl_add_u64 v[20:21], v[18:19], 2, s[4:5]
	v_fmac_f32_e32 v22, v8, v8
	global_store_dwordx4 v[20:21], v[14:17], off
	global_store_dwordx4 v[20:21], v[10:13], off offset:16
	v_fmac_f32_e32 v22, v9, v9
	v_cvt_pk_bf16_f32 v14, v14, v15
	v_cvt_pk_bf16_f32 v15, v16, v17
	v_cvt_pk_bf16_f32 v16, v10, v11
	v_pk_add_f32 v[10:11], v[2:3], v[34:35]
	v_cvt_pk_bf16_f32 v17, v12, v13
	v_fmac_f32_e32 v22, v10, v10
	v_pk_add_f32 v[12:13], v[4:5], v[36:37]
	v_fmac_f32_e32 v22, v11, v11
	v_fmac_f32_e32 v22, v12, v12
	v_fmac_f32_e32 v22, v13, v13
	ds_bpermute_b32 v2, v173, v22
	v_lshl_add_u64 v[18:19], v[18:19], 1, s[0:1]
	s_mov_b64 exec, s[54:55]
	global_store_dwordx4 v[18:19], v[14:17], off
	s_mov_b64 exec, -1
	global_store_dwordx4 v[20:21], v[6:9], off offset:512
	global_store_dwordx4 v[20:21], v[10:13], off offset:528
	v_cvt_pk_bf16_f32 v4, v6, v7
	v_cvt_pk_bf16_f32 v5, v8, v9
	s_waitcnt lgkmcnt(0)
	v_add_f32_e32 v2, v22, v2
	ds_bpermute_b32 v3, v172, v2
	v_cvt_pk_bf16_f32 v6, v10, v11
	v_cvt_pk_bf16_f32 v7, v12, v13
	s_mov_b64 exec, s[54:55]
	global_store_dwordx4 v[18:19], v[4:7], off offset:256
	s_mov_b64 exec, -1
	s_and_saveexec_b64 s[2:3], vcc
	s_cbranch_execz .LBB0_1045
	v_lshlrev_b64 v[4:5], 6, v[54:55]
	v_lshl_add_u64 v[4:5], s[6:7], 0, v[4:5]
	v_readlane_b32 s9, v255, 14
	v_lshl_add_u64 v[4:5], s[18:19], 2, v[4:5]
	s_lshl_b32 s26, s9, 2
	v_lshl_add_u64 v[4:5], v[4:5], 0, s[26:27]
	s_waitcnt lgkmcnt(0)
	v_add_f32_e32 v2, v2, v3
	global_store_dword v[4:5], v2, off
